# self-attn FIXM item: gate loads and output stores coalesced (8 lanes per row segment) via wave-private swizzled LDS transpose
# baseline (speedup 1.0000x reference)
.LBB0_898:
	s_add_i32 s9, s3, -1
	s_min_u32 s9, s9, s2
	s_lshl_b32 s9, s9, 6
	s_waitcnt vmcnt(1)
	ds_write_b128 v142, v[112:115] offset:16384
	s_waitcnt vmcnt(0)
	ds_write_b128 v142, v[116:119] offset:24576
	v_mad_u64_u32 v[64:65], s[18:19], s9, v237, v[132:133]
	global_load_dwordx4 v[120:123], v[64:65], off offset:2048
	global_load_dwordx4 v[124:127], v[136:137], off offset:-128
	ds_read_b128 v[64:67], v144 offset:8192
	ds_read_b128 v[68:71], v144 offset:12288
	ds_read_b128 v[72:75], v141 offset:8192
	ds_read_b128 v[76:79], v141 offset:12288
	v_exp_f32_e32 v151, v48
	v_exp_f32_e32 v152, v49
	s_waitcnt lgkmcnt(3)
	v_mfma_f32_32x32x16_bf16 v[16:31], v[64:67], v[80:83], v[16:31]
	v_exp_f32_e32 v153, v50
	v_add_f32_e32 v112, 0, v151
	v_add_f32_e32 v113, 0, v152
	v_exp_f32_e32 v154, v51
	ds_read_b128 v[48:51], v140 offset:8192
	ds_read_b128 v[64:67], v140 offset:12288
	v_exp_f32_e32 v155, v52
	s_waitcnt lgkmcnt(4)
	v_mfma_f32_32x32x16_bf16 v[0:15], v[68:71], v[80:83], v[0:15]
	v_exp_f32_e32 v156, v53
	v_exp_f32_e32 v159, v54
	v_exp_f32_e32 v160, v55
	v_add_f32_e32 v114, 0, v153
	v_add_f32_e32 v115, 0, v154
	v_exp_f32_e32 v162, v57
	s_waitcnt lgkmcnt(3)
	v_mfma_f32_32x32x16_bf16 v[16:31], v[72:75], v[84:87], v[16:31]
	ds_read_b128 v[68:71], v139 offset:8192
	ds_read_b128 v[80:83], v139 offset:12288
	v_add_f32_e32 v157, v155, v112
	v_add_f32_e32 v158, v156, v113
	v_add_u32_e32 v164, v143, v145
	ds_read_b128 v[52:55], v164
	ds_read_b128 v[72:75], v164 offset:4096
	v_add_f32_e32 v161, v159, v114
	s_waitcnt lgkmcnt(6)
	v_mfma_f32_32x32x16_bf16 v[0:15], v[76:79], v[84:87], v[0:15]
	v_exp_f32_e32 v77, v56
	v_add_f32_e32 v76, v160, v115
	v_exp_f32_e32 v62, v62
	v_add_u32_e32 v165, v143, v146
	ds_read_b128 v[112:115], v165
	ds_read_b128 v[116:119], v165 offset:4096
	v_cvt_pk_bf16_f32 v56, v151, v152
	s_waitcnt lgkmcnt(7)
	v_mfma_f32_32x32x16_bf16 v[16:31], v[48:51], v[88:91], v[16:31]
	v_exp_f32_e32 v49, v58
	v_exp_f32_e32 v50, v59
	v_add_f32_e32 v48, v77, v157
	v_add_f32_e32 v51, v162, v158
	v_add_f32_e32 v78, v49, v161
	v_add_f32_e32 v76, v50, v76
	s_waitcnt lgkmcnt(6)
	v_mfma_f32_32x32x16_bf16 v[0:15], v[64:67], v[88:91], v[0:15]
	v_exp_f32_e32 v60, v60
	v_add_f32_e32 v151, v62, v78
	v_exp_f32_e32 v61, v61
	v_exp_f32_e32 v63, v63
	v_cvt_pk_bf16_f32 v59, v159, v160
	v_exp_f32_e32 v160, v33
	s_waitcnt lgkmcnt(5)
	v_mfma_f32_32x32x16_bf16 v[16:31], v[68:71], v[92:95], v[16:31]
	v_cvt_pk_bf16_f32 v57, v153, v154
	v_cvt_pk_bf16_f32 v58, v155, v156
	v_add_f32_e32 v48, v60, v48
	v_add_f32_e32 v51, v61, v51
	v_cvt_pk_bf16_f32 v49, v49, v50
	s_waitcnt lgkmcnt(4)
	v_mfma_f32_32x32x16_bf16 v[0:15], v[80:83], v[92:95], v[0:15]
	v_exp_f32_e32 v95, v32
	v_add_f32_e32 v32, v63, v76
	v_add_f32_e32 v163, v160, v51
	v_add_f32_e32 v161, v95, v48
	v_cvt_pk_bf16_f32 v48, v77, v162
	v_cvt_pk_bf16_f32 v51, v62, v63
	s_waitcnt lgkmcnt(3)
	v_mfma_f32_32x32x16_bf16 v[78:93], v[52:55], v[96:99], 0
	v_cvt_pk_bf16_f32 v50, v60, v61
	v_exp_f32_e32 v60, v34
	v_exp_f32_e32 v61, v35
	v_exp_f32_e32 v36, v36
	v_exp_f32_e32 v37, v37
	v_exp_f32_e32 v38, v38
	v_exp_f32_e32 v39, v39
	s_waitcnt lgkmcnt(2)
	v_mfma_f32_32x32x16_bf16 v[62:77], v[72:75], v[96:99], 0
	v_add_u32_e32 v166, v143, v147
	ds_read_b128 v[52:55], v166
	ds_read_b128 v[152:155], v166 offset:4096
	v_add_f32_e32 v151, v60, v151
	v_add_f32_e32 v162, v61, v32
	s_waitcnt lgkmcnt(3)
	v_mfma_f32_32x32x16_bf16 v[78:93], v[112:115], v[100:103], v[78:93]
	v_add_u32_e32 v94, v143, v149
	v_add_f32_e32 v112, v36, v161
	v_add_f32_e32 v113, v37, v163
	v_add_f32_e32 v114, v38, v151
	v_exp_f32_e32 v115, v40
	v_add_f32_e32 v40, v39, v162
	ds_read_b128 v[32:35], v94
	ds_read_b128 v[156:159], v94 offset:4096
	s_waitcnt lgkmcnt(4)
	v_mfma_f32_32x32x16_bf16 v[62:77], v[116:119], v[100:103], v[62:77]
	v_exp_f32_e32 v116, v41
	v_add_f32_e32 v41, v115, v112
	s_min_u32 s9, s3, s2
	s_lshl_b32 s9, s9, 6
	v_add_f32_e32 v112, v116, v113
	s_waitcnt lgkmcnt(3)
	v_mfma_f32_32x32x16_bf16 v[78:93], v[52:55], v[104:107], v[78:93]
	v_cvt_pk_bf16_f32 v54, v36, v37
	v_exp_f32_e32 v37, v42
	v_cvt_pk_bf16_f32 v55, v38, v39
	v_exp_f32_e32 v38, v43
	v_exp_f32_e32 v39, v44
	v_exp_f32_e32 v44, v45
	v_exp_f32_e32 v45, v46
	v_exp_f32_e32 v46, v47
	v_cvt_pk_bf16_f32 v52, v95, v160
	v_cvt_pk_bf16_f32 v53, v60, v61
	v_add_f32_e32 v36, v37, v114
	v_add_f32_e32 v43, v38, v40
	v_add_f32_e32 v40, v39, v41
	v_add_f32_e32 v42, v44, v112
	v_add_f32_e32 v41, v45, v36
	v_add_f32_e32 v43, v46, v43
	v_cvt_pk_bf16_f32 v36, v115, v116
	v_cvt_pk_bf16_f32 v37, v37, v38
	v_cvt_pk_bf16_f32 v38, v39, v44
	v_cvt_pk_bf16_f32 v39, v45, v46
	s_waitcnt lgkmcnt(1)
	v_mfma_f32_32x32x16_bf16 v[78:93], v[32:35], v[108:111], v[78:93]
	s_waitcnt lgkmcnt(0)
	s_barrier
	v_mad_u64_u32 v[32:33], s[18:19], s9, v237, v[132:133]
	global_load_dwordx4 v[112:115], v[32:33], off offset:2048
	global_load_dwordx4 v[116:119], v[136:137], off
	v_add_f32_e64 v32, v40, v42
	v_add_f32_e64 v33, v41, v43
	s_waitcnt vmcnt(3)
	ds_write_b128 v142, v[120:123]
	s_waitcnt vmcnt(2)
	ds_write_b128 v142, v[124:127] offset:8192
	v_mfma_f32_32x32x16_bf16 v[62:77], v[152:155], v[104:107], v[62:77]
	v_add_f32_e32 v32, v32, v33
	v_add_f32_e32 v150, v150, v32
	s_waitcnt lgkmcnt(2)
	v_mfma_f32_32x32x16_bf16 v[62:77], v[156:159], v[108:111], v[62:77]
	ds_read_b128 v[32:35], v144 offset:24576
	ds_read_b128 v[40:43], v144 offset:28672
	ds_read_b128 v[44:47], v141 offset:24576
	ds_read_b128 v[120:123], v141 offset:28672
	v_exp_f32_e32 v60, v78
	s_waitcnt lgkmcnt(3)
	v_mfma_f32_32x32x16_bf16 v[16:31], v[32:35], v[56:59], v[16:31]
	v_exp_f32_e32 v61, v79
	v_exp_f32_e32 v95, v80
	v_add_f32_e32 v78, 0, v60
	v_exp_f32_e32 v81, v81
	v_add_f32_e32 v79, 0, v61
	ds_read_b128 v[152:155], v140 offset:24576
	ds_read_b128 v[156:159], v140 offset:28672
	s_waitcnt lgkmcnt(4)
	v_mfma_f32_32x32x16_bf16 v[0:15], v[40:43], v[56:59], v[0:15]
	v_exp_f32_e32 v82, v82
	v_exp_f32_e32 v83, v83
	v_add_f32_e32 v80, 0, v95
	v_add_f32_e32 v124, 0, v81
	v_add_f32_e32 v78, v82, v78
	v_add_f32_e32 v79, v83, v79
	s_waitcnt lgkmcnt(2)
	v_mfma_f32_32x32x16_bf16 v[0:15], v[120:123], v[48:51], v[0:15]
	ds_read_b128 v[56:59], v139 offset:24576
	ds_read_b128 v[160:163], v139 offset:28672
	ds_read_b128 v[40:43], v164 offset:16384
	ds_read_b128 v[32:35], v164 offset:20480
	v_cvt_pk_bf16_f32 v82, v82, v83
	v_exp_f32_e32 v151, v62
	v_exp_f32_e32 v64, v64
	v_exp_f32_e32 v65, v65
	v_mfma_f32_32x32x16_bf16 v[16:31], v[44:47], v[48:51], v[16:31]
	v_exp_f32_e32 v44, v84
	v_exp_f32_e32 v45, v85
	v_exp_f32_e32 v84, v86
	v_exp_f32_e32 v85, v87
	v_add_f32_e32 v46, v44, v80
	v_add_f32_e32 v47, v45, v124
	v_add_f32_e32 v48, v84, v78
	s_waitcnt lgkmcnt(4)
	v_mfma_f32_32x32x16_bf16 v[0:15], v[156:159], v[52:55], v[0:15]
	v_add_f32_e32 v49, v85, v79
	v_exp_f32_e32 v78, v88
	v_exp_f32_e32 v79, v89
	v_exp_f32_e32 v87, v92
	v_cvt_pk_bf16_f32 v83, v44, v45
	v_exp_f32_e32 v44, v90
	v_mfma_f32_32x32x16_bf16 v[16:31], v[152:155], v[52:55], v[16:31]
	v_exp_f32_e32 v45, v91
	v_exp_f32_e32 v92, v93
	v_add_f32_e32 v46, v78, v46
	v_add_f32_e32 v47, v79, v47
	ds_read_b128 v[124:127], v165 offset:16384
	ds_read_b128 v[120:123], v165 offset:20480
	s_waitcnt lgkmcnt(4)
	v_mfma_f32_32x32x16_bf16 v[0:15], v[160:163], v[36:39], v[0:15]
	v_exp_f32_e32 v160, v63
	v_cvt_pk_bf16_f32 v80, v60, v61
	v_cvt_pk_bf16_f32 v81, v95, v81
	v_add_f32_e32 v48, v44, v48
	v_add_f32_e32 v49, v45, v49
	v_add_f32_e32 v46, v87, v46
	v_add_f32_e32 v47, v92, v47
	v_mfma_f32_32x32x16_bf16 v[16:31], v[56:59], v[36:39], v[16:31]
	v_add_f32_e32 v161, v151, v48
	v_add_f32_e32 v162, v160, v49
	v_cvt_pk_bf16_f32 v84, v84, v85
	v_cvt_pk_bf16_f32 v85, v78, v79
	v_cvt_pk_bf16_f32 v86, v44, v45
	v_add_f32_e32 v78, v64, v46
	v_add_f32_e32 v79, v65, v47
	s_waitcnt lgkmcnt(3)
	v_mfma_f32_32x32x16_bf16 v[48:63], v[40:43], v[96:99], 0
	ds_read_b128 v[88:91], v166 offset:16384
	ds_read_b128 v[152:155], v166 offset:20480
	v_exp_f32_e32 v66, v66
	v_exp_f32_e32 v67, v67
	v_exp_f32_e32 v68, v68
	v_exp_f32_e32 v69, v69
	v_cvt_pk_bf16_f32 v87, v87, v92
	s_waitcnt lgkmcnt(4)
	v_mfma_f32_32x32x16_bf16 v[32:47], v[32:35], v[96:99], 0
	ds_read_b128 v[156:159], v94 offset:16384
	ds_read_b128 v[92:95], v94 offset:20480
	v_add_f32_e32 v161, v66, v161
	v_add_f32_e32 v162, v67, v162
	v_add_f32_e32 v78, v68, v78
	v_add_f32_e32 v79, v69, v79
	s_waitcnt lgkmcnt(5)
	v_mfma_f32_32x32x16_bf16 v[48:63], v[124:127], v[100:103], v[48:63]
	v_exp_f32_e32 v70, v70
	v_exp_f32_e32 v71, v71
	s_add_i32 s9, s3, 2
	s_add_i32 s3, s3, -2
	v_lshl_add_u64 v[136:137], v[136:137], 0, s[22:23]
	s_waitcnt lgkmcnt(4)
	v_mfma_f32_32x32x16_bf16 v[32:47], v[120:123], v[100:103], v[32:47]
	v_add_f32_e32 v120, v70, v161
	v_add_f32_e32 v121, v71, v162
	s_cmp_lt_u32 s3, s2
	s_mov_b32 s3, s9
	s_waitcnt lgkmcnt(3)
	v_mfma_f32_32x32x16_bf16 v[48:63], v[88:91], v[104:107], v[48:63]
	v_cvt_pk_bf16_f32 v91, v68, v69
	v_exp_f32_e32 v68, v72
	v_exp_f32_e32 v69, v73
	v_exp_f32_e32 v72, v74
	v_exp_f32_e32 v73, v75
	v_exp_f32_e32 v74, v76
	v_exp_f32_e32 v75, v77
	s_waitcnt lgkmcnt(2)
	v_mfma_f32_32x32x16_bf16 v[32:47], v[152:155], v[104:107], v[32:47]
	v_cvt_pk_bf16_f32 v88, v151, v160
	v_cvt_pk_bf16_f32 v89, v64, v65
	v_cvt_pk_bf16_f32 v90, v66, v67
	v_add_f32_e32 v65, v68, v78
	v_add_f32_e32 v67, v69, v79
	s_waitcnt lgkmcnt(1)
	v_mfma_f32_32x32x16_bf16 v[48:63], v[156:159], v[108:111], v[48:63]
	v_add_f32_e32 v64, v72, v120
	v_add_f32_e32 v66, v73, v121
	v_add_f32_e32 v65, v74, v65
	v_add_f32_e32 v67, v75, v67
	s_waitcnt lgkmcnt(0)
	v_mfma_f32_32x32x16_bf16 v[32:47], v[92:95], v[108:111], v[32:47]
	v_cvt_pk_bf16_f32 v92, v70, v71
	v_cvt_pk_bf16_f32 v93, v68, v69
	v_cvt_pk_bf16_f32 v94, v72, v73
	v_cvt_pk_bf16_f32 v95, v74, v75
	v_add_f32_e64 v64, v64, v66
	v_add_f32_e64 v65, v65, v67
	s_waitcnt lgkmcnt(0)
	s_barrier
	v_add_f32_e32 v64, v64, v65
	v_add_f32_e32 v150, v150, v64
	s_cbranch_scc1 .LBB0_898
	v_ashrrev_i32_e32 v64, 1, v129
	v_and_or_b32 v132, v64, s88, v148
	v_bfe_u32 v66, v250, 3, 3
	v_lshrrev_b32_e32 v67, 6, v250
	v_lshl_or_b32 v66, v67, 5, v66
	v_mov_b64_e32 v[64:65], s[12:13]
	v_mad_i64_i32 v[64:65], s[2:3], v66, s33, v[64:65]
	v_and_b32_e32 v66, 7, v250
	v_lshlrev_b32_e32 v66, 4, v66
	v_mov_b32_e32 v67, 0
	v_lshlrev_b32_e32 v176, 4, v138
	s_waitcnt vmcnt(1)
	ds_write_b128 v142, v[112:115] offset:16384
	s_waitcnt vmcnt(0)
	ds_write_b128 v142, v[116:119] offset:24576
	v_lshl_add_u64 v[64:65], v[64:65], 0, v[66:67]
	s_mov_b64 s[2:3], 0x9000
	global_load_dwordx4 v[124:127], v[64:65], off offset:2560
	v_lshl_add_u64 v[64:65], v[64:65], 0, s[2:3]
	global_load_dwordx4 v[120:123], v[64:65], off offset:2560
	v_lshl_add_u64 v[64:65], v[64:65], 0, s[2:3]
	global_load_dwordx4 v[116:119], v[64:65], off offset:2560
	v_lshl_add_u64 v[64:65], v[64:65], 0, s[2:3]
	global_load_dwordx4 v[112:115], v[64:65], off offset:2560
	v_mov_b64_e32 v[64:65], s[14:15]
	v_mad_i64_i32 v[64:65], s[2:3], v132, s33, v[64:65]
	v_and_b32_e32 v66, 16, v131
	v_mov_b32_e32 v67, v177
	v_lshl_add_u64 v[64:65], v[64:65], 0, v[66:67]
	global_load_dwordx4 v[96:99], v[64:65], off offset:1024
	global_load_dwordx4 v[100:103], v[64:65], off offset:1056
	global_load_dwordx4 v[104:107], v[64:65], off offset:1088
	global_load_dwordx4 v[108:111], v[64:65], off offset:1120
	v_lshl_add_u64 v[64:65], s[34:35], 0, v[134:135]
	v_lshlrev_b32_e32 v76, 1, v130
	v_mov_b32_e32 v77, v177
	v_lshl_add_u64 v[72:73], v[64:65], 0, v[76:77]
	s_mov_b32 s2, 0x48000
	v_add_co_u32_e32 v68, vcc, s2, v72
	s_mov_b32 s2, 0x90000
	s_nop 0
	v_addc_co_u32_e32 v69, vcc, 0, v73, vcc
	global_load_dwordx4 v[64:67], v[72:73], off offset:2048
	v_ashrrev_i32_e32 v133, 31, v132
	global_load_dwordx4 v[68:71], v[68:69], off offset:2048
	v_add_co_u32_e32 v72, vcc, s2, v72
	v_mad_i64_i32 v[78:79], s[2:3], s8, v128, 0
	v_lshl_add_u64 v[78:79], v[78:79], 1, s[10:11]
	v_addc_co_u32_e32 v73, vcc, 0, v73, vcc
	v_lshl_add_u64 v[76:77], v[78:79], 0, v[76:77]
	global_load_dwordx4 v[72:75], v[72:73], off offset:2048
	s_nop 0
	global_load_dwordx4 v[76:79], v[76:77], off
	ds_read_b128 v[128:131], v144 offset:8192
	ds_read_b128 v[134:137], v144 offset:12288
	ds_read_b128 v[146:149], v141 offset:8192
	ds_read_b128 v[152:155], v141 offset:12288
	v_exp_f32_e32 v138, v48
	v_exp_f32_e32 v142, v49
	s_waitcnt lgkmcnt(3)
	v_mfma_f32_32x32x16_bf16 v[16:31], v[128:131], v[80:83], v[16:31]
	v_exp_f32_e32 v151, v50
	v_add_f32_e32 v143, 0, v138
	v_add_f32_e32 v145, 0, v142
	v_exp_f32_e32 v156, v51
	ds_read_b128 v[48:51], v140 offset:8192
	ds_read_b128 v[128:131], v140 offset:12288
	v_exp_f32_e32 v52, v52
	s_waitcnt lgkmcnt(4)
	v_mfma_f32_32x32x16_bf16 v[0:15], v[134:137], v[80:83], v[0:15]
	v_exp_f32_e32 v53, v53
	v_exp_f32_e32 v54, v54
	v_exp_f32_e32 v55, v55
	v_add_f32_e32 v157, 0, v151
	v_add_f32_e32 v158, 0, v156
	v_add_f32_e32 v143, v52, v143
	s_waitcnt lgkmcnt(3)
	v_mfma_f32_32x32x16_bf16 v[16:31], v[146:149], v[84:87], v[16:31]
	v_add_f32_e32 v145, v53, v145
	v_add_f32_e32 v146, v54, v157
	ds_read_b128 v[80:83], v139 offset:8192
	ds_read_b128 v[134:137], v139 offset:12288
	v_exp_f32_e32 v56, v56
	v_exp_f32_e32 v57, v57
	v_exp_f32_e32 v58, v58
	s_waitcnt lgkmcnt(4)
	v_mfma_f32_32x32x16_bf16 v[0:15], v[152:155], v[84:87], v[0:15]
	v_add_f32_e32 v84, v55, v158
	v_exp_f32_e32 v59, v59
	v_exp_f32_e32 v60, v60
	v_exp_f32_e32 v32, v32
	v_exp_f32_e32 v33, v33
	v_exp_f32_e32 v34, v34
	s_waitcnt lgkmcnt(3)
	v_mfma_f32_32x32x16_bf16 v[16:31], v[48:51], v[88:91], v[16:31]
	v_cvt_pk_bf16_f32 v51, v54, v55
	v_exp_f32_e32 v54, v61
	v_exp_f32_e32 v55, v62
	v_exp_f32_e32 v61, v63
	v_exp_f32_e32 v35, v35
	v_add_f32_e32 v85, v56, v143
	v_add_f32_e32 v86, v57, v145
	v_add_f32_e32 v87, v58, v146
	v_add_f32_e32 v84, v59, v84
	v_cvt_pk_bf16_f32 v48, v138, v142
	v_cvt_pk_bf16_f32 v49, v151, v156
	v_cvt_pk_bf16_f32 v50, v52, v53
	v_add_f32_e32 v52, v60, v85
	v_add_f32_e32 v53, v54, v86
	v_add_f32_e32 v62, v55, v87
	v_add_f32_e32 v63, v61, v84
	v_exp_f32_e32 v36, v36
	v_exp_f32_e32 v37, v37
	v_exp_f32_e32 v38, v38
	v_exp_f32_e32 v39, v39
	s_waitcnt lgkmcnt(1)
	v_mfma_f32_32x32x16_bf16 v[16:31], v[80:83], v[92:95], v[16:31]
	v_add_f32_e32 v80, v32, v52
	v_add_f32_e32 v81, v33, v53
	v_cvt_pk_bf16_f32 v52, v56, v57
	v_cvt_pk_bf16_f32 v53, v58, v59
	v_cvt_pk_bf16_f32 v54, v60, v54
	v_cvt_pk_bf16_f32 v55, v55, v61
	v_add_f32_e32 v56, v34, v62
	v_add_f32_e32 v57, v35, v63
	v_exp_f32_e32 v40, v40
	v_add_f32_e32 v58, v36, v80
	v_add_f32_e32 v59, v37, v81
	v_add_f32_e32 v56, v38, v56
	v_exp_f32_e32 v41, v41
	v_add_f32_e32 v57, v39, v57
	v_mfma_f32_32x32x16_bf16 v[0:15], v[128:131], v[88:91], v[0:15]
	v_cvt_pk_bf16_f32 v32, v32, v33
	v_cvt_pk_bf16_f32 v33, v34, v35
	v_cvt_pk_bf16_f32 v34, v36, v37
	v_exp_f32_e32 v37, v42
	v_cvt_pk_bf16_f32 v35, v38, v39
	v_exp_f32_e32 v38, v43
	v_exp_f32_e32 v39, v44
	v_exp_f32_e32 v43, v45
	v_exp_f32_e32 v44, v46
	v_exp_f32_e32 v45, v47
	v_add_f32_e32 v58, v40, v58
	v_add_f32_e32 v59, v41, v59
	v_add_f32_e32 v36, v37, v56
	v_add_f32_e32 v42, v38, v57
	v_add_f32_e32 v56, v39, v58
	v_add_f32_e32 v58, v43, v59
	s_waitcnt lgkmcnt(0)
	v_mfma_f32_32x32x16_bf16 v[0:15], v[134:137], v[92:95], v[0:15]
	v_add_f32_e32 v57, v44, v36
	v_add_f32_e32 v59, v45, v42
	v_cvt_pk_bf16_f32 v36, v40, v41
	v_cvt_pk_bf16_f32 v37, v37, v38
	v_cvt_pk_bf16_f32 v38, v39, v43
	v_cvt_pk_bf16_f32 v39, v44, v45
	s_waitcnt lgkmcnt(0)
	s_barrier
	ds_read_b128 v[40:43], v144 offset:24576
	ds_read_b128 v[44:47], v144 offset:28672
	s_waitcnt lgkmcnt(1)
	v_mfma_f32_32x32x16_bf16 v[16:31], v[40:43], v[48:51], v[16:31]
	s_waitcnt lgkmcnt(0)
	v_mfma_f32_32x32x16_bf16 v[0:15], v[44:47], v[48:51], v[0:15]
	ds_read_b128 v[40:43], v141 offset:24576
	ds_read_b128 v[44:47], v141 offset:28672
	s_waitcnt lgkmcnt(1)
	v_mfma_f32_32x32x16_bf16 v[16:31], v[40:43], v[52:55], v[16:31]
	s_waitcnt lgkmcnt(0)
	v_mfma_f32_32x32x16_bf16 v[0:15], v[44:47], v[52:55], v[0:15]
	ds_read_b128 v[40:43], v140 offset:24576
	ds_read_b128 v[44:47], v140 offset:28672
	s_waitcnt lgkmcnt(1)
	v_mfma_f32_32x32x16_bf16 v[16:31], v[40:43], v[32:35], v[16:31]
	s_waitcnt lgkmcnt(0)
	v_mfma_f32_32x32x16_bf16 v[0:15], v[44:47], v[32:35], v[0:15]
	ds_read_b128 v[32:35], v139 offset:24576
	ds_read_b128 v[40:43], v139 offset:28672
	s_waitcnt lgkmcnt(1)
	v_mfma_f32_32x32x16_bf16 v[16:31], v[32:35], v[36:39], v[16:31]
	v_add_f32_e64 v32, v56, v58
	v_add_f32_e64 v33, v57, v59
	v_add_f32_e32 v32, v32, v33
	v_add_f32_e32 v32, v150, v32
	v_mov_b32_e32 v33, v32
	s_nop 1
	v_permlane32_swap_b32_e32 v32, v33
	v_add_f32_e32 v32, v32, v33
	v_div_scale_f32 v33, s[2:3], v32, v32, 1.0
	v_rcp_f32_e32 v34, v33
	s_waitcnt lgkmcnt(0)
	v_mfma_f32_32x32x16_bf16 v[0:15], v[40:43], v[36:39], v[0:15]
	v_and_b32_e32 v85, 63, v250
	v_lshrrev_b32_e32 v86, 3, v85
	v_and_b32_e32 v80, 7, v85
	v_xor_b32_e32 v80, v80, v86
	v_lshlrev_b32_e32 v80, 4, v80
	v_lshl_or_b32 v80, v86, 7, v80
	v_lshrrev_b32_e32 v86, 6, v250
	v_lshlrev_b32_e32 v86, 12, v86
	v_add_u32_e32 v86, 0x10000, v86
	v_or_b32_e32 v80, v80, v86
	v_and_b32_e32 v81, 31, v85
	v_lshrrev_b32_e32 v85, 5, v85
	v_and_b32_e32 v87, 7, v81
	v_xor_b32_e32 v87, v87, v85
	v_lshlrev_b32_e32 v87, 4, v87
	v_lshl_or_b32 v81, v81, 7, v87
	v_or_b32_e32 v81, v81, v86
	v_xor_b32_e32 v82, 32, v81
	v_xor_b32_e32 v83, 64, v81
	v_xor_b32_e32 v84, 0x60, v81
	s_waitcnt vmcnt(8)
	ds_write_b128 v80, v[124:127]
	ds_write_b128 v80, v[120:123] offset:1024
	ds_write_b128 v80, v[116:119] offset:2048
	ds_write_b128 v80, v[112:115] offset:3072
	s_waitcnt lgkmcnt(0)
	ds_read_b128 v[124:127], v81
	ds_read_b128 v[120:123], v82
	ds_read_b128 v[116:119], v83
	ds_read_b128 v[112:115], v84
	s_waitcnt lgkmcnt(0)
	s_waitcnt vmcnt(11)
	v_mov_b32_e32 v40, v127
	s_nop 1
	v_permlane32_swap_b32_e32 v125, v40
	v_fma_f32 v35, -v33, v34, 1.0
	v_fmac_f32_e32 v34, v35, v34
	v_div_scale_f32 v35, vcc, 1.0, v32, 1.0
	v_mul_f32_e32 v36, v35, v34
	v_fma_f32 v37, -v33, v36, v35
	v_fmac_f32_e32 v36, v37, v34
	v_fma_f32 v33, -v33, v36, v35
	v_div_fmas_f32 v33, v33, v34, v36
	v_mov_b32_e32 v35, v126
	v_div_fixup_f32 v34, v33, v32, 1.0
	s_nop 0
	v_permlane32_swap_b32_e32 v124, v35
	v_lshlrev_b32_e32 v38, 16, v124
	v_and_b32_e32 v39, 0xffff0000, v124
	v_mul_f32_e32 v16, v16, v34
	v_mul_f32_e32 v17, v17, v34
	v_mul_f32_e32 v18, v18, v34
	v_mul_f32_e32 v19, v19, v34
	v_mul_f32_e32 v16, v16, v38
	v_mul_f32_e32 v17, v17, v39
	v_lshlrev_b32_e32 v38, 16, v125
	v_and_b32_e32 v39, 0xffff0000, v125
	v_mul_f32_e32 v18, v18, v38
	v_mul_f32_e32 v19, v19, v39
	v_cvt_pk_bf16_f32 v16, v16, v17
	v_cvt_pk_bf16_f32 v17, v18, v19
	v_lshlrev_b32_e32 v18, 16, v35
	v_and_b32_e32 v19, 0xffff0000, v35
	v_mul_f32_e32 v20, v20, v34
	v_mul_f32_e32 v21, v21, v34
	v_mul_f32_e32 v22, v22, v34
	v_mul_f32_e32 v23, v23, v34
	v_mul_f32_e32 v18, v20, v18
	v_mul_f32_e32 v19, v21, v19
	v_lshlrev_b32_e32 v20, 16, v40
	v_and_b32_e32 v21, 0xffff0000, v40
	v_lshlrev_b64 v[32:33], 11, v[132:133]
	v_mul_f32_e32 v20, v22, v20
	v_mul_f32_e32 v21, v23, v21
	v_lshl_add_u64 v[32:33], s[6:7], 0, v[32:33]
	v_cvt_pk_bf16_f32 v18, v18, v19
	v_cvt_pk_bf16_f32 v19, v20, v21
	s_waitcnt vmcnt(10)
	v_mov_b32_e32 v22, v122
	v_lshl_add_u64 v[36:37], v[32:33], 0, v[176:177]
	v_permlane32_swap_b32_e32 v16, v18
	v_permlane32_swap_b32_e32 v17, v19
	v_permlane32_swap_b32_e32 v120, v22
	v_mov_b32_e32 v23, v123
	ds_write_b128 v81, v[16:19]
	s_nop 0
	v_permlane32_swap_b32_e32 v121, v23
	v_lshlrev_b32_e32 v16, 16, v120
	v_and_b32_e32 v17, 0xffff0000, v120
	v_mul_f32_e32 v18, v24, v34
	v_mul_f32_e32 v19, v25, v34
	v_mul_f32_e32 v20, v26, v34
	v_mul_f32_e32 v21, v27, v34
	v_mul_f32_e32 v16, v18, v16
	v_mul_f32_e32 v17, v19, v17
	v_lshlrev_b32_e32 v18, 16, v121
	v_and_b32_e32 v19, 0xffff0000, v121
	v_mul_f32_e32 v18, v20, v18
	v_mul_f32_e32 v19, v21, v19
	v_cvt_pk_bf16_f32 v16, v16, v17
	v_cvt_pk_bf16_f32 v17, v18, v19
	v_lshlrev_b32_e32 v18, 16, v22
	v_and_b32_e32 v19, 0xffff0000, v22
	v_mul_f32_e32 v20, v28, v34
	v_mul_f32_e32 v21, v29, v34
	v_mul_f32_e32 v0, v0, v34
	v_mul_f32_e32 v1, v1, v34
	v_mul_f32_e32 v18, v20, v18
	v_mul_f32_e32 v19, v21, v19
	v_lshlrev_b32_e32 v20, 16, v23
	v_and_b32_e32 v21, 0xffff0000, v23
	v_mul_f32_e32 v22, v30, v34
	v_mul_f32_e32 v23, v31, v34
	v_cvt_pk_bf16_f32 v18, v18, v19
	v_mul_f32_e32 v20, v22, v20
	v_mul_f32_e32 v21, v23, v21
	s_nop 0
	v_permlane32_swap_b32_e32 v16, v18
	v_cvt_pk_bf16_f32 v19, v20, v21
	s_nop 1
	v_permlane32_swap_b32_e32 v17, v19
	ds_write_b128 v82, v[16:19]
	v_mul_f32_e32 v2, v2, v34
	v_mul_f32_e32 v3, v3, v34
	v_mul_f32_e32 v4, v4, v34
	v_mul_f32_e32 v5, v5, v34
	s_waitcnt vmcnt(11)
	v_mov_b32_e32 v18, v118
	s_nop 1
	v_permlane32_swap_b32_e32 v116, v18
	v_mov_b32_e32 v19, v119
	s_nop 1
	v_permlane32_swap_b32_e32 v117, v19
	v_lshlrev_b32_e32 v16, 16, v116
	v_and_b32_e32 v17, 0xffff0000, v116
	v_mul_f32_e32 v0, v0, v16
	v_mul_f32_e32 v1, v1, v17
	v_lshlrev_b32_e32 v16, 16, v117
	v_and_b32_e32 v17, 0xffff0000, v117
	v_mul_f32_e32 v2, v2, v16
	v_mul_f32_e32 v3, v3, v17
	v_cvt_pk_bf16_f32 v0, v0, v1
	v_cvt_pk_bf16_f32 v1, v2, v3
	v_lshlrev_b32_e32 v2, 16, v18
	v_and_b32_e32 v3, 0xffff0000, v18
	v_mul_f32_e32 v2, v4, v2
	v_mul_f32_e32 v3, v5, v3
	v_lshlrev_b32_e32 v4, 16, v19
	v_and_b32_e32 v5, 0xffff0000, v19
	v_mul_f32_e32 v6, v6, v34
	v_mul_f32_e32 v7, v7, v34
	v_cvt_pk_bf16_f32 v2, v2, v3
	v_mul_f32_e32 v4, v6, v4
	v_mul_f32_e32 v5, v7, v5
	s_waitcnt vmcnt(10)
	v_mov_b32_e32 v6, v114
	v_cvt_pk_bf16_f32 v3, v4, v5
	v_permlane32_swap_b32_e32 v0, v2
	s_nop 0
	v_permlane32_swap_b32_e32 v1, v3
	v_permlane32_swap_b32_e32 v112, v6
	v_mov_b32_e32 v7, v115
	ds_write_b128 v83, v[0:3]
	s_nop 0
	v_permlane32_swap_b32_e32 v113, v7
	v_lshlrev_b32_e32 v0, 16, v112
	v_and_b32_e32 v1, 0xffff0000, v112
	v_mul_f32_e32 v2, v8, v34
	v_mul_f32_e32 v3, v9, v34
	v_mul_f32_e32 v4, v10, v34
	v_mul_f32_e32 v5, v11, v34
	v_mul_f32_e32 v0, v2, v0
	v_mul_f32_e32 v1, v3, v1
	v_lshlrev_b32_e32 v2, 16, v113
	v_and_b32_e32 v3, 0xffff0000, v113
	v_mul_f32_e32 v2, v4, v2
	v_mul_f32_e32 v3, v5, v3
	v_cvt_pk_bf16_f32 v0, v0, v1
	v_cvt_pk_bf16_f32 v1, v2, v3
	v_lshlrev_b32_e32 v2, 16, v6
	v_and_b32_e32 v3, 0xffff0000, v6
	v_mul_f32_e32 v4, v12, v34
	v_mul_f32_e32 v5, v13, v34
	s_mov_b64 s[2:3], 0x200
	v_mul_f32_e32 v2, v4, v2
	v_mul_f32_e32 v3, v5, v3
	v_lshlrev_b32_e32 v4, 16, v7
	v_and_b32_e32 v5, 0xffff0000, v7
	v_mul_f32_e32 v6, v14, v34
	v_mul_f32_e32 v7, v15, v34
	v_cvt_pk_bf16_f32 v2, v2, v3
	v_mul_f32_e32 v4, v6, v4
	v_mul_f32_e32 v5, v7, v5
	v_lshl_add_u64 v[32:33], v[36:37], 0, s[2:3]
	v_cvt_pk_bf16_f32 v3, v4, v5
	v_permlane32_swap_b32_e32 v0, v2
	s_nop 0
	v_permlane32_swap_b32_e32 v1, v3
	s_nop 0
	ds_write_b128 v84, v[0:3]
	v_bfe_u32 v85, v250, 3, 3
	v_lshrrev_b32_e32 v86, 6, v250
	v_lshl_or_b32 v85, v86, 5, v85
	v_lshlrev_b32_e32 v86, 11, v85
	v_and_b32_e32 v85, 7, v250
	v_lshl_or_b32 v86, v85, 4, v86
	v_mov_b32_e32 v87, 0
	v_lshl_add_u64 v[32:33], s[6:7], 0, v[86:87]
	s_mov_b64 s[2:3], 0x4000
	s_waitcnt lgkmcnt(0)
	ds_read_b128 v[112:115], v80
	ds_read_b128 v[116:119], v80 offset:1024
	ds_read_b128 v[120:123], v80 offset:2048
	ds_read_b128 v[124:127], v80 offset:3072
	s_waitcnt lgkmcnt(3)
	global_store_dwordx4 v[32:33], v[112:115], off offset:512
	v_lshl_add_u64 v[32:33], v[32:33], 0, s[2:3]
	s_waitcnt lgkmcnt(2)
	global_store_dwordx4 v[32:33], v[116:119], off offset:512
	v_lshl_add_u64 v[32:33], v[32:33], 0, s[2:3]
	s_waitcnt lgkmcnt(1)
	global_store_dwordx4 v[32:33], v[120:123], off offset:512
	v_lshl_add_u64 v[32:33], v[32:33], 0, s[2:3]
	s_waitcnt lgkmcnt(0)
	global_store_dwordx4 v[32:33], v[124:127], off offset:512
	s_or_b64 exec, exec, s[44:45]
	s_andn2_b64 vcc, exec, s[0:1]
	s_mov_b32 s8, s20
	s_cbranch_vccz .LBB0_900
	s_branch .LBB0_877
